# P0: odd waves run the x->bf16 conversion first and the weight transposes afterwards (bandwidth-bound and latency-bound sections overlap across waves)
# baseline (speedup 1.0000x reference)
; #define LAS __attribute__((address_space(3)))
; __device__ __forceinline__ void phase_prep(const Args& a, LAS unsigned char* lds, int wid, int lane) {
;     unsigned char* ws = a.ws;
;     LAS float* scr = (LAS float*)(lds + wid * 16384);
;     const int gw = blockIdx.x * NWAVES + wid, NGW = gridDim.x * NWAVES;
;     const int gt = blockIdx.x * (NWAVES * 64) + threadIdx.x, NGT = gridDim.x * NWAVES * 64;
;     if (threadIdx.x == 0) ((int*)(ws + WS_XCC))[blockIdx.x] = (int)(__builtin_amdgcn_s_getreg((3 << 11) | 20) & 0xF);
;     if (blockIdx.x == 0) { unsigned* bw = (unsigned*)(ws + WS_BAR); for (int i = threadIdx.x; i < XCD_BAR_WORDS; i += NWAVES * 64) bw[i] = 0u; }
;     { float* z = (float*)(ws + WS_SSQ) + M; for (int i = gt; i < 4 * M; i += NGT) z[i] = 0.f; }
;     { float* rt = (float*)(ws + WS_ROPE);
;       for (int i = gt; i < T * 32; i += NGT) { const int t = i >> 5, k = i & 31;
;           const float invf = (float)exp2(-(double)k * (13.287712379549449 / 32.0));
;           const float ang = (float)t * invf;
;           double rev = (double)ang * 0.15915494309189535; rev -= floor(rev);
;           const float fr = (float)rev;
;           rt[2 * i] = __builtin_amdgcn_cosf(fr); rt[2 * i + 1] = __builtin_amdgcn_sinf(fr); } }
;     constexpr int I0 = 16 * 96, I1 = 16 * 32, I2 = 16 * 176, I3 = 44 * 32, I4 = 16 * 48, I5 = 8 * 32, I6 = I2, I7 = I3;
;     constexpr int NIT = I0 + I1 + I2 + I3 + I4 + I5 + I6 + I7;
;     for (int it = gw; it < NIT; it += NGW) {
;         int r = it;
;         if (r < I0) { tr_job(r, a.w_in_0, nullptr, a.mix_norm_0, (bf16_t*)(ws + WS_WIN0), 1024, 3072, 3072, 1, 0, scr, lane); continue; } r -= I0;
.LBB0_21:
	s_or_b64 exec, exec, s[6:7]
	s_load_dwordx16 s[72:87], s[0:1], 0x0
	s_load_dwordx16 s[4:19], s[0:1], 0x40
	s_load_dwordx16 s[36:51], s[0:1], 0x80
	s_lshl_b32 s1, s96, 3
	s_lshr_b32 s0, s22, 6
	v_and_b32_e32 v212, 63, v200
	s_mov_b32 s97, s0
	s_waitcnt lgkmcnt(0)
	v_writelane_b32 v254, s36, 9
	s_add_i32 s3, s0, s1
	v_lshrrev_b32_e32 v128, 5, v212
	v_writelane_b32 v254, s37, 10
	v_writelane_b32 v254, s38, 11
	v_writelane_b32 v254, s39, 12
	v_writelane_b32 v254, s40, 13
	v_writelane_b32 v254, s41, 14
	v_writelane_b32 v254, s42, 15
	v_writelane_b32 v254, s43, 16
	v_writelane_b32 v254, s44, 17
	v_writelane_b32 v254, s45, 18
	v_writelane_b32 v254, s46, 19
	v_writelane_b32 v254, s47, 20
	v_writelane_b32 v254, s48, 21
	v_writelane_b32 v254, s49, 22
	v_writelane_b32 v254, s50, 23
	v_writelane_b32 v254, s51, 24
	v_writelane_b32 v254, s22, 6
	v_writelane_b32 v254, s1, 7
	v_lshlrev_b32_e32 v141, 3, v200
	v_readlane_b32 s28, v254, 0
	v_readlane_b32 s30, v254, 2
	s_lshl_b32 s0, s30, 3
	s_cmpk_gt_i32 s3, 0x2cff
	v_readlane_b32 s29, v254, 1
	v_readlane_b32 s31, v254, 3
	v_writelane_b32 v254, s0, 8
	s_cbranch_scc1 .LBB0_317
	s_mov_b32 s32, 0
	s_bitcmp1_b32 s3, 0
	s_cbranch_scc0 .Lwp_entry
	s_mov_b32 s32, 1
	v_writelane_b32 v253, s4, 42
	v_writelane_b32 v253, s5, 43
	v_writelane_b32 v253, s6, 44
	v_writelane_b32 v253, s7, 45
	v_writelane_b32 v253, s8, 46
	v_writelane_b32 v253, s9, 47
	v_writelane_b32 v253, s10, 48
	v_writelane_b32 v253, s11, 49
	v_writelane_b32 v253, s12, 50
	v_writelane_b32 v253, s13, 51
	v_writelane_b32 v253, s14, 52
	v_writelane_b32 v253, s15, 53
	v_writelane_b32 v253, s16, 54
	v_writelane_b32 v253, s17, 55
	v_writelane_b32 v253, s18, 56
	v_writelane_b32 v253, s19, 57
	v_writelane_b32 v253, s26, 58
	v_readlane_b32 s36, v254, 0
	v_readlane_b32 s37, v254, 1
	v_readlane_b32 s38, v254, 2
	s_nop 4
	s_branch .LBB0_322
.Lwp_entry:
	v_writelane_b32 v253, s0, 0
	v_writelane_b32 v253, s1, 1
	v_writelane_b32 v253, s2, 2
	v_writelane_b32 v253, s20, 3
	v_writelane_b32 v253, s21, 4
	v_writelane_b32 v253, s22, 5
	v_writelane_b32 v253, s23, 6
	v_writelane_b32 v253, s27, 7
	v_writelane_b32 v253, s28, 8
	v_writelane_b32 v253, s29, 9
	v_writelane_b32 v253, s30, 10
	v_writelane_b32 v253, s31, 11
	v_writelane_b32 v253, s33, 12
	v_writelane_b32 v253, s35, 13
	v_writelane_b32 v253, s52, 14
	v_writelane_b32 v253, s53, 15
	v_writelane_b32 v253, s54, 16
	v_writelane_b32 v253, s55, 17
	v_writelane_b32 v253, s56, 18
	v_writelane_b32 v253, s57, 19
	v_writelane_b32 v253, s58, 20
	v_writelane_b32 v253, s59, 21
	v_writelane_b32 v253, s60, 22
	v_writelane_b32 v253, s61, 23
	v_writelane_b32 v253, s62, 24
	v_writelane_b32 v253, s63, 25
	s_mov_b64 s[0:1], exec
	v_writelane_b32 v253, s0, 40
	v_writelane_b32 v253, s1, 41
	s_mov_b64 exec, -1
	v_readlane_b32 s62, v254, 0
	v_readlane_b32 s63, v254, 1
	v_readlane_b32 s21, v254, 8
	s_mov_b32 s20, s3
	v_lshrrev_b32_e32 v146, 5, v212
	v_and_b32_e32 v147, 31, v212
	v_lshlrev_b32_e32 v147, 2, v147
	s_lshl_b32 s0, s97, 14
	v_mov_b32_e32 v148, 0x84
	v_mad_u32_u24 v148, v146, v148, v147
	v_add_u32_e32 v148, s0, v148
	v_and_b32_e32 v149, 7, v212
	v_lshrrev_b32_e32 v150, 3, v212
	v_mov_b32_e32 v151, 0x420
	v_mul_u32_u24_e32 v151, v149, v151
	v_lshl_add_u32 v151, v150, 2, v151
	v_add_u32_e32 v151, s0, v151
	v_lshlrev_b32_e32 v152, 5, v149
	v_lshlrev_b32_e32 v155, 4, v149

; __device__ __forceinline__ unsigned pk2(float lo, float hi) { return f2bf(lo) | (f2bf(hi) << 16); }
; __device__ __forceinline__ void phase_prep(const Args& a, LAS unsigned char* lds, int wid, int lane) {
;     ...
;     { bf16_t* XN = (bf16_t*)(ws + WS_XN); float* ssq0 = (float*)(ws + WS_SSQ);
;       for (int m0 = 4 * gw; m0 < M; m0 += 4 * NGW) {
;           f32x4 v[4][4];
; #pragma unroll
;           for (int r = 0; r < 4; ++r)
; #pragma unroll
;               for (int j = 0; j < 4; ++j) v[r][j] = ((const f32x4*)(a.x + (size_t)(m0 + r) * D) + lane)[64 * j];
; #pragma unroll
;           for (int r = 0; r < 4; ++r) { float s = 0.f; unsigned long long* o8 = (unsigned long long*)(XN + (size_t)(m0 + r) * D) + lane;
; #pragma unroll
;               for (int j = 0; j < 4; ++j) { const f32x4 x = v[r][j]; s += (x.x * x.x + x.y * x.y) + (x.z * x.z + x.w * x.w);
;                   o8[64 * j] = (unsigned long long)pk2(x.x, x.y) | ((unsigned long long)pk2(x.z, x.w) << 32); }
;               s = wsum(s); if (lane == 0) ssq0[m0 + r] = s; } } }
.LBB0_322:
	s_cmpk_lt_i32 s3, 0x2000
	s_cselect_b64 s[8:9], -1, 0
	s_cmp_eq_u32 s32, 2
	s_cbranch_scc1 .LBB0_333
	s_cmpk_gt_i32 s3, 0x1fff
	v_mbcnt_lo_u32_b32 v129, -1, 0
	v_lshlrev_b32_e32 v202, 4, v212
	s_cbranch_scc1 .Lxn_exit
	v_mbcnt_hi_u32_b32 v2, -1, v129
	v_and_b32_e32 v1, 64, v2
	v_add_u32_e32 v3, 64, v1
	v_xor_b32_e32 v1, 1, v2
	v_cmp_lt_i32_e32 vcc, v1, v3
	v_xor_b32_e32 v4, 2, v2
	s_lshl_b32 s6, s3, 2
	v_cndmask_b32_e32 v1, v2, v1, vcc
	v_cmp_lt_i32_e32 vcc, v4, v3
	s_lshl_b32 s10, s38, 5
	s_ashr_i32 s7, s6, 31
	v_cndmask_b32_e32 v4, v2, v4, vcc
	v_lshlrev_b32_e32 v58, 2, v4
	v_xor_b32_e32 v4, 4, v2
	v_cmp_lt_i32_e32 vcc, v4, v3
	s_lshl_b64 s[0:1], s[6:7], 11
	s_ashr_i32 s11, s10, 31
	v_cndmask_b32_e32 v4, v2, v4, vcc
	v_lshlrev_b32_e32 v59, 2, v4
	v_xor_b32_e32 v4, 8, v2
	v_cmp_lt_i32_e32 vcc, v4, v3
	v_lshl_or_b32 v50, v212, 3, s0
	v_mov_b32_e32 v51, s1
	v_cndmask_b32_e32 v4, v2, v4, vcc
	v_lshlrev_b32_e32 v60, 2, v4
	v_xor_b32_e32 v4, 16, v2
	v_cmp_lt_i32_e32 vcc, v4, v3
	s_lshl_b64 s[12:13], s[10:11], 11
	s_lshl_b64 s[0:1], s[6:7], 12
	v_cndmask_b32_e32 v4, v2, v4, vcc
	v_lshlrev_b32_e32 v61, 2, v4
	v_xor_b32_e32 v4, 32, v2
	v_cmp_lt_i32_e32 vcc, v4, v3
	s_add_u32 s0, s72, s0
	v_mov_b32_e32 v203, 0
	v_cndmask_b32_e32 v2, v2, v4, vcc
	s_addc_u32 s1, s73, s1
	v_lshlrev_b32_e32 v62, 2, v2
	v_lshl_add_u64 v[2:3], s[0:1], 0, v[202:203]
	s_mov_b64 s[0:1], 0x3c00
	v_lshlrev_b32_e32 v1, 2, v1
	v_cmp_eq_u32_e64 s[4:5], 0, v212
	v_lshl_add_u64 v[52:53], v[2:3], 0, s[0:1]
	s_lshl_b64 s[14:15], s[10:11], 12
	s_lshl_b64 s[16:17], s[6:7], 2
	s_lshl_b64 s[18:19], s[10:11], 2
	s_movk_i32 s2, 0x7fff
	s_mov_b32 s7, 0xffff0000
	s_mov_b32 s11, 0x3800000
	s_mov_b32 s22, 0x3801000
	s_branch .LBB0_325

; __device__ __forceinline__ void phase_prep(const Args& a, LAS unsigned char* lds, int wid, int lane) {
;     ...
;     for (int it = gw; it < NIT; it += NGW) {
;         int r = it;
;         if (r < I0) { tr_job(r, a.w_in_0, nullptr, a.mix_norm_0, (bf16_t*)(ws + WS_WIN0), 1024, 3072, 3072, 1, 0, scr, lane); continue; } r -= I0;
.Lxn_exit:
	s_cmp_eq_u32 s32, 0
	s_cbranch_scc1 .LBB0_333
	v_readlane_b32 s4, v253, 42
	v_readlane_b32 s5, v253, 43
	v_readlane_b32 s6, v253, 44
	v_readlane_b32 s7, v253, 45
	v_readlane_b32 s8, v253, 46
	v_readlane_b32 s9, v253, 47
	v_readlane_b32 s10, v253, 48
	v_readlane_b32 s11, v253, 49
	v_readlane_b32 s12, v253, 50
	v_readlane_b32 s13, v253, 51
	v_readlane_b32 s14, v253, 52
	v_readlane_b32 s15, v253, 53
	v_readlane_b32 s16, v253, 54
	v_readlane_b32 s17, v253, 55
	v_readlane_b32 s18, v253, 56
	v_readlane_b32 s19, v253, 57
	v_readlane_b32 s26, v253, 58
	s_nop 4
	s_mov_b32 s32, 2
	s_branch .Lwp_entry
